# pool window sums vectorised: thread = 4 channels x 8 tokens, rows read once with ds_read_b64
# speedup vs baseline: 1.0107x; 1.0107x over previous
; __device__ __forceinline__ unsigned cvtpk(float lo, float hi) { f32x2_t v = {lo, hi}; bf16x2_t b = __builtin_convertvector(v, bf16x2_t); return __builtin_bit_cast(unsigned, b); }
; #define LAS __attribute__((address_space(3)))
; #define LDS_WAIT() asm volatile("s_waitcnt lgkmcnt(0)" ::: "memory")
; #define MFMA32(a, b, c) __builtin_amdgcn_mfma_f32_32x32x16_bf16((a), (b), (c), 0, 0, 0)
; __device__ __forceinline__ void pool_units(const Ptrs& P, LAS unsigned char* lds, int bx, int G, int tid, int wave, int lane) {
;     ...
;         {
;             f32x16 acc[2];
; #pragma unroll
;             for (int j = 0; j < 2; ++j)
; #pragma unroll
;                 for (int i = 0; i < 16; ++i) acc[j][i] = 0.f;
; #pragma unroll
;             for (int ks = 0; ks < 8; ++ks) {
;                 const bf16x8_t bt = *(const LAS bf16x8_t*)(lds + PL_A + (32 * rb + r) * PL_AP + (16 * ks + 8 * hh) * 2);
; #pragma unroll
;                 for (int j = 0; j < 2; ++j) acc[j] = MFMA32(wa[j][ks], bt, acc[j]);
;             }
;             bf16_t* PMr = (bf16_t*)(ws + WS_PM) + (size_t)(tt * 128 + 32 * rb + r) * PMP + g * 128;
; #pragma unroll
;             for (int j = 0; j < 2; ++j)
; #pragma unroll
;                 for (int g4 = 0; g4 < 4; ++g4) { const int d = 32 * (2 * (wave & 1) + j) + 8 * g4 + 4 * hh; const f32x4 sc = *(const f32x4*)(P.pool_scale + g * 128 + d);
;                     u32x2 w; w.x = cvtpk(acc[j][4 * g4] * sc[0], acc[j][4 * g4 + 1] * sc[1]); w.y = cvtpk(acc[j][4 * g4 + 2] * sc[2], acc[j][4 * g4 + 3] * sc[3]);
;                     *(u32x2*)(PMr + d) = w; }
;         }
;         LDS_WAIT(); __builtin_amdgcn_s_barrier(); asm volatile("" ::: "memory");
.Lpool_mfma:
	s_waitcnt lgkmcnt(0)
	s_barrier
	ds_read_b128 v[0:3], v213 offset:36864
	ds_read_b128 v[214:217], v213 offset:36896
	s_waitcnt vmcnt(15) lgkmcnt(1)
	v_mfma_f32_32x32x16_bf16 v[16:31], v[80:83], v[0:3], 0
	v_lshl_add_u64 v[234:235], v[230:231], 0, s[6:7]
	s_lshl_b32 s6, s19, 9
	v_lshl_add_u64 v[236:237], v[130:131], 0, s[6:7]
	s_waitcnt vmcnt(7)
	v_mfma_f32_32x32x16_bf16 v[0:15], v[112:115], v[0:3], 0
	s_waitcnt lgkmcnt(0)
	v_mfma_f32_32x32x16_bf16 v[16:31], v[76:79], v[214:217], v[16:31]
	s_waitcnt vmcnt(6)
	v_mfma_f32_32x32x16_bf16 v[0:15], v[108:111], v[214:217], v[0:15]
	ds_read_b128 v[214:217], v213 offset:36928
	ds_read_b128 v[218:221], v213 offset:36960
	s_waitcnt lgkmcnt(1)
	v_mfma_f32_32x32x16_bf16 v[16:31], v[72:75], v[214:217], v[16:31]
	s_waitcnt vmcnt(5)
	v_mfma_f32_32x32x16_bf16 v[0:15], v[104:107], v[214:217], v[0:15]
	s_waitcnt lgkmcnt(0)
	v_mfma_f32_32x32x16_bf16 v[16:31], v[68:71], v[218:221], v[16:31]
	s_waitcnt vmcnt(4)
	v_mfma_f32_32x32x16_bf16 v[0:15], v[100:103], v[218:221], v[0:15]
	ds_read_b128 v[214:217], v213 offset:36992
	ds_read_b128 v[218:221], v213 offset:37024
	ds_read_b128 v[222:225], v213 offset:37056
	ds_read_b128 v[226:229], v213 offset:37088
	v_lshl_add_u64 v[230:231], v[234:235], 0, v[132:133]
	s_waitcnt lgkmcnt(3)
	v_mfma_f32_32x32x16_bf16 v[16:31], v[64:67], v[214:217], v[16:31]
	s_waitcnt lgkmcnt(2)
	v_mfma_f32_32x32x16_bf16 v[16:31], v[60:63], v[218:221], v[16:31]
	s_waitcnt lgkmcnt(1)
	v_mfma_f32_32x32x16_bf16 v[16:31], v[56:59], v[222:225], v[16:31]
	s_waitcnt lgkmcnt(0)
	v_mfma_f32_32x32x16_bf16 v[16:31], v[52:55], v[226:229], v[16:31]
	s_waitcnt vmcnt(0)
	v_mfma_f32_32x32x16_bf16 v[0:15], v[96:99], v[214:217], v[0:15]
	v_mfma_f32_32x32x16_bf16 v[0:15], v[92:95], v[218:221], v[0:15]
	v_mfma_f32_32x32x16_bf16 v[0:15], v[88:91], v[222:225], v[0:15]
	v_mfma_f32_32x32x16_bf16 v[0:15], v[84:87], v[226:229], v[0:15]
	global_load_dwordx4 v[214:217], v[236:237], off offset:128
	global_load_dwordx4 v[218:221], v[236:237], off offset:160
	global_load_dwordx4 v[222:225], v[236:237], off offset:192
	global_load_dwordx4 v[226:229], v[236:237], off offset:224
	s_nop 7
	v_mul_f32_e64 v16, v16, v238
	v_mul_f32_e64 v17, v17, v239
	v_mul_f32_e64 v18, v18, v240
	v_mul_f32_e64 v19, v19, v241
	v_cvt_pk_bf16_f32 v16, v16, v17
	v_cvt_pk_bf16_f32 v17, v18, v19
	global_store_dwordx2 v[230:231], v[16:17], off
	v_mul_f32_e64 v20, v20, v242
	v_mul_f32_e64 v21, v21, v243
	v_mul_f32_e64 v22, v22, v244
	v_mul_f32_e64 v23, v23, v245
	v_cvt_pk_bf16_f32 v20, v20, v21
	v_cvt_pk_bf16_f32 v21, v22, v23
	global_store_dwordx2 v[230:231], v[20:21], off offset:16
	v_mul_f32_e64 v24, v24, v246
	v_mul_f32_e64 v25, v25, v247
	v_mul_f32_e64 v26, v26, v248
	v_mul_f32_e64 v27, v27, v249
	v_cvt_pk_bf16_f32 v24, v24, v25
	v_cvt_pk_bf16_f32 v25, v26, v27
	global_store_dwordx2 v[230:231], v[24:25], off offset:32
	v_mul_f32_e64 v28, v28, v252
	v_mul_f32_e64 v29, v29, v253
	v_mul_f32_e64 v30, v30, v254
	v_mul_f32_e64 v31, v31, v255
	v_cvt_pk_bf16_f32 v28, v28, v29
	v_cvt_pk_bf16_f32 v29, v30, v31
	global_store_dwordx2 v[230:231], v[28:29], off offset:48
	s_waitcnt vmcnt(4)
	v_pk_mul_f32 v[0:1], v[0:1], v[214:215]
	v_pk_mul_f32 v[2:3], v[2:3], v[216:217]
	v_cvt_pk_bf16_f32 v0, v0, v1
	v_cvt_pk_bf16_f32 v1, v2, v3
	global_store_dwordx2 v[230:231], v[0:1], off offset:64
	v_pk_mul_f32 v[4:5], v[4:5], v[218:219]
	v_pk_mul_f32 v[6:7], v[6:7], v[220:221]
	v_cvt_pk_bf16_f32 v4, v4, v5
	v_cvt_pk_bf16_f32 v5, v6, v7
	global_store_dwordx2 v[230:231], v[4:5], off offset:80
	v_pk_mul_f32 v[8:9], v[8:9], v[222:223]
	v_pk_mul_f32 v[10:11], v[10:11], v[224:225]
	v_cvt_pk_bf16_f32 v8, v8, v9
	v_cvt_pk_bf16_f32 v9, v10, v11
	global_store_dwordx2 v[230:231], v[8:9], off offset:96
	v_pk_mul_f32 v[12:13], v[12:13], v[226:227]
	v_pk_mul_f32 v[14:15], v[14:15], v[228:229]
	v_cvt_pk_bf16_f32 v12, v12, v13
	v_cvt_pk_bf16_f32 v13, v14, v15
	global_store_dwordx2 v[230:231], v[12:13], off offset:112
	s_waitcnt lgkmcnt(0)
	s_barrier
	s_cbranch_vccnz .LBB9_444

; __device__ __forceinline__ float bf2f(bf16_t v) { return __uint_as_float((unsigned)v << 16); }
; __device__ __forceinline__ unsigned cvtpk(float lo, float hi) { f32x2_t v = {lo, hi}; bf16x2_t b = __builtin_convertvector(v, bf16x2_t); return __builtin_bit_cast(unsigned, b); }
; #define LAS __attribute__((address_space(3)))
; __device__ __forceinline__ void pool_units(const Ptrs& P, LAS unsigned char* lds, int bx, int G, int tid, int wave, int lane) {
;     ...
;         {
;             const int c = tid & 127, tl0 = (tid >> 7) * 32, w2 = 1 << g; const LAS bf16_t* U = (const LAS bf16_t*)(lds + PL_U) + c; float sum = 0.f;
;             for (int j = tl0 - w2; j < tl0 + w2; ++j) sum += bf2f(U[(j + 8) * 128]);
;             for (int tl = tl0; tl < tl0 + 32; ++tl) {
;                 const int ts = ts0 + tl, lo = ts - w2 < 0 ? 0 : ts - w2, hi = ts + w2 > SEQ ? SEQ : ts + w2;
;                 const float d = sum * __builtin_amdgcn_rcpf((float)(hi - lo)) - bf2f(U[(tl + 8) * 128]);
;                 *(LAS bf16_t*)(lds + PL_A + tl * PL_AP + c * 2) = (bf16_t)(cvtpk(d, 0.f) & 0xffffu);
;                 sum += bf2f(U[(tl + w2 + 8) * 128]) - bf2f(U[(tl - w2 + 8) * 128]);
;             }
;         }
.LBB9_434:
	s_lshl_b32 s2, s20, 5
	s_and_b32 s3, s2, 0xf80
	s_and_b32 s2, s2, 0xffffff80
	v_add_u32_e32 v230, s2, v139
	v_ashrrev_i32_e32 v231, 31, v230
	v_lshlrev_b64 v[230:231], 11, v[230:231]
	v_lshl_add_u64 v[230:231], s[8:9], 0, v[230:231]
	v_mov_b32_e32 v133, v119
	v_and_b32_e32 v152, 31, v208
	v_lshrrev_b32_e32 v153, 5, v208
	v_lshlrev_b32_e32 v152, 3, v152
	v_lshl_add_u32 v150, v153, 11, v152
	v_mul_u32_u24_e32 v151, 0x880, v153
	v_add_u32_e32 v151, v151, v152
	v_lshl_add_u32 v148, v153, 3, s3
	s_mov_b32 s20, s18
	s_cmp_eq_u32 s19, 0
	s_cbranch_scc1 .Lpw_0
	s_cmp_eq_u32 s19, 1
	s_cbranch_scc1 .Lpw_1
	s_cmp_eq_u32 s19, 2
	s_cbranch_scc1 .Lpw_2
	ds_read_b64 v[0:1], v150 offset:0
	ds_read_b64 v[2:3], v150 offset:256
	ds_read_b64 v[4:5], v150 offset:512
	ds_read_b64 v[6:7], v150 offset:768
	ds_read_b64 v[8:9], v150 offset:1024
	ds_read_b64 v[10:11], v150 offset:1280
	ds_read_b64 v[12:13], v150 offset:1536
	ds_read_b64 v[14:15], v150 offset:1792
	ds_read_b64 v[16:17], v150 offset:2048
	ds_read_b64 v[18:19], v150 offset:2304
	ds_read_b64 v[20:21], v150 offset:2560
	ds_read_b64 v[22:23], v150 offset:2816
	ds_read_b64 v[24:25], v150 offset:3072
	ds_read_b64 v[26:27], v150 offset:3328
	ds_read_b64 v[28:29], v150 offset:3584
	ds_read_b64 v[30:31], v150 offset:3840
	ds_read_b64 v[214:215], v150 offset:4096
	ds_read_b64 v[216:217], v150 offset:4352
	ds_read_b64 v[218:219], v150 offset:4608
	ds_read_b64 v[220:221], v150 offset:4864
	ds_read_b64 v[222:223], v150 offset:5120
	ds_read_b64 v[224:225], v150 offset:5376
	ds_read_b64 v[226:227], v150 offset:5632
	ds_read_b64 v[228:229], v150 offset:5888
	s_waitcnt lgkmcnt(0)
	v_lshlrev_b32_e32 v140, 16, v0
	v_and_b32_e32 v141, 0xffff0000, v0
	v_lshlrev_b32_e32 v142, 16, v1
	v_and_b32_e32 v143, 0xffff0000, v1
	v_lshlrev_b32_e32 v144, 16, v2
	v_and_b32_e32 v145, 0xffff0000, v2
	v_lshlrev_b32_e32 v146, 16, v3
	v_and_b32_e32 v147, 0xffff0000, v3
	v_add_f32_e32 v140, v140, v144
	v_add_f32_e32 v141, v141, v145
	v_add_f32_e32 v142, v142, v146
	v_add_f32_e32 v143, v143, v147
	v_lshlrev_b32_e32 v144, 16, v4
	v_and_b32_e32 v145, 0xffff0000, v4
	v_lshlrev_b32_e32 v146, 16, v5
	v_and_b32_e32 v147, 0xffff0000, v5
	v_add_f32_e32 v140, v140, v144
	v_add_f32_e32 v141, v141, v145
	v_add_f32_e32 v142, v142, v146
	v_add_f32_e32 v143, v143, v147
	v_lshlrev_b32_e32 v144, 16, v6
	v_and_b32_e32 v145, 0xffff0000, v6
	v_lshlrev_b32_e32 v146, 16, v7
	v_and_b32_e32 v147, 0xffff0000, v7
	v_add_f32_e32 v140, v140, v144
	v_add_f32_e32 v141, v141, v145
	v_add_f32_e32 v142, v142, v146
	v_add_f32_e32 v143, v143, v147
	v_lshlrev_b32_e32 v144, 16, v8
	v_and_b32_e32 v145, 0xffff0000, v8
	v_lshlrev_b32_e32 v146, 16, v9
	v_and_b32_e32 v147, 0xffff0000, v9
	v_add_f32_e32 v140, v140, v144
	v_add_f32_e32 v141, v141, v145
	v_add_f32_e32 v142, v142, v146
	v_add_f32_e32 v143, v143, v147
	v_lshlrev_b32_e32 v144, 16, v10
	v_and_b32_e32 v145, 0xffff0000, v10
	v_lshlrev_b32_e32 v146, 16, v11
	v_and_b32_e32 v147, 0xffff0000, v11
	v_add_f32_e32 v140, v140, v144
	v_add_f32_e32 v141, v141, v145
	v_add_f32_e32 v142, v142, v146
	v_add_f32_e32 v143, v143, v147
	v_lshlrev_b32_e32 v144, 16, v12
	v_and_b32_e32 v145, 0xffff0000, v12
	v_lshlrev_b32_e32 v146, 16, v13
	v_and_b32_e32 v147, 0xffff0000, v13
	v_add_f32_e32 v140, v140, v144
	v_add_f32_e32 v141, v141, v145
	v_add_f32_e32 v142, v142, v146
	v_add_f32_e32 v143, v143, v147
	v_lshlrev_b32_e32 v144, 16, v14
	v_and_b32_e32 v145, 0xffff0000, v14
	v_lshlrev_b32_e32 v146, 16, v15
	v_and_b32_e32 v147, 0xffff0000, v15
	v_add_f32_e32 v140, v140, v144
	v_add_f32_e32 v141, v141, v145
	v_add_f32_e32 v142, v142, v146
	v_add_f32_e32 v143, v143, v147
	v_lshlrev_b32_e32 v144, 16, v16
	v_and_b32_e32 v145, 0xffff0000, v16
	v_lshlrev_b32_e32 v146, 16, v17
	v_and_b32_e32 v147, 0xffff0000, v17
	v_add_f32_e32 v140, v140, v144
	v_add_f32_e32 v141, v141, v145
	v_add_f32_e32 v142, v142, v146
	v_add_f32_e32 v143, v143, v147
	v_lshlrev_b32_e32 v144, 16, v18
	v_and_b32_e32 v145, 0xffff0000, v18
	v_lshlrev_b32_e32 v146, 16, v19
	v_and_b32_e32 v147, 0xffff0000, v19
	v_add_f32_e32 v140, v140, v144
	v_add_f32_e32 v141, v141, v145
	v_add_f32_e32 v142, v142, v146
	v_add_f32_e32 v143, v143, v147
	v_lshlrev_b32_e32 v144, 16, v20
	v_and_b32_e32 v145, 0xffff0000, v20
	v_lshlrev_b32_e32 v146, 16, v21
	v_and_b32_e32 v147, 0xffff0000, v21
	v_add_f32_e32 v140, v140, v144
	v_add_f32_e32 v141, v141, v145
	v_add_f32_e32 v142, v142, v146
	v_add_f32_e32 v143, v143, v147
	v_lshlrev_b32_e32 v144, 16, v22
	v_and_b32_e32 v145, 0xffff0000, v22
	v_lshlrev_b32_e32 v146, 16, v23
	v_and_b32_e32 v147, 0xffff0000, v23
	v_add_f32_e32 v140, v140, v144
	v_add_f32_e32 v141, v141, v145
	v_add_f32_e32 v142, v142, v146
	v_add_f32_e32 v143, v143, v147
	v_lshlrev_b32_e32 v144, 16, v24
	v_and_b32_e32 v145, 0xffff0000, v24
	v_lshlrev_b32_e32 v146, 16, v25
	v_and_b32_e32 v147, 0xffff0000, v25
	v_add_f32_e32 v140, v140, v144
	v_add_f32_e32 v141, v141, v145
	v_add_f32_e32 v142, v142, v146
	v_add_f32_e32 v143, v143, v147
	v_lshlrev_b32_e32 v144, 16, v26
	v_and_b32_e32 v145, 0xffff0000, v26
	v_lshlrev_b32_e32 v146, 16, v27
	v_and_b32_e32 v147, 0xffff0000, v27
	v_add_f32_e32 v140, v140, v144
	v_add_f32_e32 v141, v141, v145
	v_add_f32_e32 v142, v142, v146
	v_add_f32_e32 v143, v143, v147
	v_lshlrev_b32_e32 v144, 16, v28
	v_and_b32_e32 v145, 0xffff0000, v28
	v_lshlrev_b32_e32 v146, 16, v29
	v_and_b32_e32 v147, 0xffff0000, v29
	v_add_f32_e32 v140, v140, v144
	v_add_f32_e32 v141, v141, v145
	v_add_f32_e32 v142, v142, v146
	v_add_f32_e32 v143, v143, v147
	v_lshlrev_b32_e32 v144, 16, v30
	v_and_b32_e32 v145, 0xffff0000, v30
	v_lshlrev_b32_e32 v146, 16, v31
	v_and_b32_e32 v147, 0xffff0000, v31
; __device__ __forceinline__ float bf2f(bf16_t v) { return __uint_as_float((unsigned)v << 16); }
; __device__ __forceinline__ unsigned cvtpk(float lo, float hi) { f32x2_t v = {lo, hi}; bf16x2_t b = __builtin_convertvector(v, bf16x2_t); return __builtin_bit_cast(unsigned, b); }
; #define LAS __attribute__((address_space(3)))
; __device__ __forceinline__ void pool_units(const Ptrs& P, LAS unsigned char* lds, int bx, int G, int tid, int wave, int lane) {
;     ...
;         {
;             const int c = tid & 127, tl0 = (tid >> 7) * 32, w2 = 1 << g; const LAS bf16_t* U = (const LAS bf16_t*)(lds + PL_U) + c; float sum = 0.f;
;             for (int j = tl0 - w2; j < tl0 + w2; ++j) sum += bf2f(U[(j + 8) * 128]);
;             for (int tl = tl0; tl < tl0 + 32; ++tl) {
;                 const int ts = ts0 + tl, lo = ts - w2 < 0 ? 0 : ts - w2, hi = ts + w2 > SEQ ? SEQ : ts + w2;
;                 const float d = sum * __builtin_amdgcn_rcpf((float)(hi - lo)) - bf2f(U[(tl + 8) * 128]);
;                 *(LAS bf16_t*)(lds + PL_A + tl * PL_AP + c * 2) = (bf16_t)(cvtpk(d, 0.f) & 0xffffu);
;                 sum += bf2f(U[(tl + w2 + 8) * 128]) - bf2f(U[(tl - w2 + 8) * 128]);
;             }
;         }
	v_add_f32_e32 v140, v140, v144
	v_add_f32_e32 v141, v141, v145
	v_add_f32_e32 v142, v142, v146
	v_add_f32_e32 v143, v143, v147
	v_subrev_u32_e32 v152, 8, v148
	v_max_i32_e32 v152, 0, v152
	v_add_u32_e32 v149, 8, v148
	v_min_u32_e32 v149, 0x1000, v149
	v_sub_u32_e32 v149, v149, v152
	v_cvt_f32_i32_e32 v149, v149
	v_rcp_iflag_f32_e32 v149, v149
	v_lshlrev_b32_e32 v144, 16, v16
	v_and_b32_e32 v145, 0xffff0000, v16
	v_lshlrev_b32_e32 v146, 16, v17
	v_and_b32_e32 v147, 0xffff0000, v17
	v_fma_f32 v144, v149, v140, -v144
	v_fma_f32 v145, v149, v141, -v145
	v_fma_f32 v146, v149, v142, -v146
	v_fma_f32 v147, v149, v143, -v147
	v_cvt_pk_bf16_f32 v154, v144, v145
	v_cvt_pk_bf16_f32 v155, v146, v147
	ds_write_b64 v151, v[154:155] offset:36864
	v_lshlrev_b32_e32 v144, 16, v214
	v_and_b32_e32 v145, 0xffff0000, v214
	v_lshlrev_b32_e32 v146, 16, v215
	v_and_b32_e32 v147, 0xffff0000, v215
	v_add_f32_e32 v140, v140, v144
	v_add_f32_e32 v141, v141, v145
	v_add_f32_e32 v142, v142, v146
	v_add_f32_e32 v143, v143, v147
	v_lshlrev_b32_e32 v144, 16, v0
	v_and_b32_e32 v145, 0xffff0000, v0
	v_lshlrev_b32_e32 v146, 16, v1
	v_and_b32_e32 v147, 0xffff0000, v1
	v_sub_f32_e32 v140, v140, v144
	v_sub_f32_e32 v141, v141, v145
	v_sub_f32_e32 v142, v142, v146
	v_sub_f32_e32 v143, v143, v147
	v_add_u32_e32 v148, 1, v148
	v_subrev_u32_e32 v152, 8, v148
	v_max_i32_e32 v152, 0, v152
	v_add_u32_e32 v149, 8, v148
	v_min_u32_e32 v149, 0x1000, v149
	v_sub_u32_e32 v149, v149, v152
	v_cvt_f32_i32_e32 v149, v149
	v_rcp_iflag_f32_e32 v149, v149
	v_lshlrev_b32_e32 v144, 16, v18
	v_and_b32_e32 v145, 0xffff0000, v18
	v_lshlrev_b32_e32 v146, 16, v19
	v_and_b32_e32 v147, 0xffff0000, v19
	v_fma_f32 v144, v149, v140, -v144
	v_fma_f32 v145, v149, v141, -v145
	v_fma_f32 v146, v149, v142, -v146
	v_fma_f32 v147, v149, v143, -v147
	v_cvt_pk_bf16_f32 v154, v144, v145
	v_cvt_pk_bf16_f32 v155, v146, v147
	ds_write_b64 v151, v[154:155] offset:37136
	v_lshlrev_b32_e32 v144, 16, v216
	v_and_b32_e32 v145, 0xffff0000, v216
	v_lshlrev_b32_e32 v146, 16, v217
	v_and_b32_e32 v147, 0xffff0000, v217
	v_add_f32_e32 v140, v140, v144
	v_add_f32_e32 v141, v141, v145
	v_add_f32_e32 v142, v142, v146
	v_add_f32_e32 v143, v143, v147
	v_lshlrev_b32_e32 v144, 16, v2
	v_and_b32_e32 v145, 0xffff0000, v2
	v_lshlrev_b32_e32 v146, 16, v3
	v_and_b32_e32 v147, 0xffff0000, v3
	v_sub_f32_e32 v140, v140, v144
	v_sub_f32_e32 v141, v141, v145
	v_sub_f32_e32 v142, v142, v146
	v_sub_f32_e32 v143, v143, v147
	v_add_u32_e32 v148, 1, v148
	v_subrev_u32_e32 v152, 8, v148
	v_max_i32_e32 v152, 0, v152
	v_add_u32_e32 v149, 8, v148
	v_min_u32_e32 v149, 0x1000, v149
	v_sub_u32_e32 v149, v149, v152
	v_cvt_f32_i32_e32 v149, v149
	v_rcp_iflag_f32_e32 v149, v149
	v_lshlrev_b32_e32 v144, 16, v20
	v_and_b32_e32 v145, 0xffff0000, v20
	v_lshlrev_b32_e32 v146, 16, v21
	v_and_b32_e32 v147, 0xffff0000, v21
	v_fma_f32 v144, v149, v140, -v144
	v_fma_f32 v145, v149, v141, -v145
	v_fma_f32 v146, v149, v142, -v146
	v_fma_f32 v147, v149, v143, -v147
	v_cvt_pk_bf16_f32 v154, v144, v145
	v_cvt_pk_bf16_f32 v155, v146, v147
	ds_write_b64 v151, v[154:155] offset:37408
	v_lshlrev_b32_e32 v144, 16, v218
	v_and_b32_e32 v145, 0xffff0000, v218
	v_lshlrev_b32_e32 v146, 16, v219
	v_and_b32_e32 v147, 0xffff0000, v219
	v_add_f32_e32 v140, v140, v144
	v_add_f32_e32 v141, v141, v145
	v_add_f32_e32 v142, v142, v146
	v_add_f32_e32 v143, v143, v147
	v_lshlrev_b32_e32 v144, 16, v4
	v_and_b32_e32 v145, 0xffff0000, v4
	v_lshlrev_b32_e32 v146, 16, v5
	v_and_b32_e32 v147, 0xffff0000, v5
	v_sub_f32_e32 v140, v140, v144
	v_sub_f32_e32 v141, v141, v145
	v_sub_f32_e32 v142, v142, v146
	v_sub_f32_e32 v143, v143, v147
	v_add_u32_e32 v148, 1, v148
	v_subrev_u32_e32 v152, 8, v148
	v_max_i32_e32 v152, 0, v152
	v_add_u32_e32 v149, 8, v148
	v_min_u32_e32 v149, 0x1000, v149
	v_sub_u32_e32 v149, v149, v152
	v_cvt_f32_i32_e32 v149, v149
	v_rcp_iflag_f32_e32 v149, v149
	v_lshlrev_b32_e32 v144, 16, v22
	v_and_b32_e32 v145, 0xffff0000, v22
	v_lshlrev_b32_e32 v146, 16, v23
	v_and_b32_e32 v147, 0xffff0000, v23
	v_fma_f32 v144, v149, v140, -v144
	v_fma_f32 v145, v149, v141, -v145
	v_fma_f32 v146, v149, v142, -v146
	v_fma_f32 v147, v149, v143, -v147
	v_cvt_pk_bf16_f32 v154, v144, v145
	v_cvt_pk_bf16_f32 v155, v146, v147
	ds_write_b64 v151, v[154:155] offset:37680
	v_lshlrev_b32_e32 v144, 16, v220
	v_and_b32_e32 v145, 0xffff0000, v220
	v_lshlrev_b32_e32 v146, 16, v221
	v_and_b32_e32 v147, 0xffff0000, v221
	v_add_f32_e32 v140, v140, v144
	v_add_f32_e32 v141, v141, v145
	v_add_f32_e32 v142, v142, v146
	v_add_f32_e32 v143, v143, v147
	v_lshlrev_b32_e32 v144, 16, v6
	v_and_b32_e32 v145, 0xffff0000, v6
	v_lshlrev_b32_e32 v146, 16, v7
	v_and_b32_e32 v147, 0xffff0000, v7
	v_sub_f32_e32 v140, v140, v144
	v_sub_f32_e32 v141, v141, v145
	v_sub_f32_e32 v142, v142, v146
	v_sub_f32_e32 v143, v143, v147
	v_add_u32_e32 v148, 1, v148
	v_subrev_u32_e32 v152, 8, v148
	v_max_i32_e32 v152, 0, v152
	v_add_u32_e32 v149, 8, v148
	v_min_u32_e32 v149, 0x1000, v149
	v_sub_u32_e32 v149, v149, v152
	v_cvt_f32_i32_e32 v149, v149
	v_rcp_iflag_f32_e32 v149, v149
	v_lshlrev_b32_e32 v144, 16, v24
	v_and_b32_e32 v145, 0xffff0000, v24
	v_lshlrev_b32_e32 v146, 16, v25
	v_and_b32_e32 v147, 0xffff0000, v25
	v_fma_f32 v144, v149, v140, -v144
	v_fma_f32 v145, v149, v141, -v145
	v_fma_f32 v146, v149, v142, -v146
	v_fma_f32 v147, v149, v143, -v147
	v_cvt_pk_bf16_f32 v154, v144, v145
	v_cvt_pk_bf16_f32 v155, v146, v147
	ds_write_b64 v151, v[154:155] offset:37952
	v_lshlrev_b32_e32 v144, 16, v222
	v_and_b32_e32 v145, 0xffff0000, v222
	v_lshlrev_b32_e32 v146, 16, v223
	v_and_b32_e32 v147, 0xffff0000, v223
	v_add_f32_e32 v140, v140, v144
; __device__ __forceinline__ float bf2f(bf16_t v) { return __uint_as_float((unsigned)v << 16); }
; __device__ __forceinline__ unsigned cvtpk(float lo, float hi) { f32x2_t v = {lo, hi}; bf16x2_t b = __builtin_convertvector(v, bf16x2_t); return __builtin_bit_cast(unsigned, b); }
; #define LAS __attribute__((address_space(3)))
; __device__ __forceinline__ void pool_units(const Ptrs& P, LAS unsigned char* lds, int bx, int G, int tid, int wave, int lane) {
;     ...
;         {
;             const int c = tid & 127, tl0 = (tid >> 7) * 32, w2 = 1 << g; const LAS bf16_t* U = (const LAS bf16_t*)(lds + PL_U) + c; float sum = 0.f;
;             for (int j = tl0 - w2; j < tl0 + w2; ++j) sum += bf2f(U[(j + 8) * 128]);
;             for (int tl = tl0; tl < tl0 + 32; ++tl) {
;                 const int ts = ts0 + tl, lo = ts - w2 < 0 ? 0 : ts - w2, hi = ts + w2 > SEQ ? SEQ : ts + w2;
;                 const float d = sum * __builtin_amdgcn_rcpf((float)(hi - lo)) - bf2f(U[(tl + 8) * 128]);
;                 *(LAS bf16_t*)(lds + PL_A + tl * PL_AP + c * 2) = (bf16_t)(cvtpk(d, 0.f) & 0xffffu);
;                 sum += bf2f(U[(tl + w2 + 8) * 128]) - bf2f(U[(tl - w2 + 8) * 128]);
;             }
;         }
	v_add_f32_e32 v141, v141, v145
	v_add_f32_e32 v142, v142, v146
	v_add_f32_e32 v143, v143, v147
	v_lshlrev_b32_e32 v144, 16, v8
	v_and_b32_e32 v145, 0xffff0000, v8
	v_lshlrev_b32_e32 v146, 16, v9
	v_and_b32_e32 v147, 0xffff0000, v9
	v_sub_f32_e32 v140, v140, v144
	v_sub_f32_e32 v141, v141, v145
	v_sub_f32_e32 v142, v142, v146
	v_sub_f32_e32 v143, v143, v147
	v_add_u32_e32 v148, 1, v148
	v_subrev_u32_e32 v152, 8, v148
	v_max_i32_e32 v152, 0, v152
	v_add_u32_e32 v149, 8, v148
	v_min_u32_e32 v149, 0x1000, v149
	v_sub_u32_e32 v149, v149, v152
	v_cvt_f32_i32_e32 v149, v149
	v_rcp_iflag_f32_e32 v149, v149
	v_lshlrev_b32_e32 v144, 16, v26
	v_and_b32_e32 v145, 0xffff0000, v26
	v_lshlrev_b32_e32 v146, 16, v27
	v_and_b32_e32 v147, 0xffff0000, v27
	v_fma_f32 v144, v149, v140, -v144
	v_fma_f32 v145, v149, v141, -v145
	v_fma_f32 v146, v149, v142, -v146
	v_fma_f32 v147, v149, v143, -v147
	v_cvt_pk_bf16_f32 v154, v144, v145
	v_cvt_pk_bf16_f32 v155, v146, v147
	ds_write_b64 v151, v[154:155] offset:38224
	v_lshlrev_b32_e32 v144, 16, v224
	v_and_b32_e32 v145, 0xffff0000, v224
	v_lshlrev_b32_e32 v146, 16, v225
	v_and_b32_e32 v147, 0xffff0000, v225
	v_add_f32_e32 v140, v140, v144
	v_add_f32_e32 v141, v141, v145
	v_add_f32_e32 v142, v142, v146
	v_add_f32_e32 v143, v143, v147
	v_lshlrev_b32_e32 v144, 16, v10
	v_and_b32_e32 v145, 0xffff0000, v10
	v_lshlrev_b32_e32 v146, 16, v11
	v_and_b32_e32 v147, 0xffff0000, v11
	v_sub_f32_e32 v140, v140, v144
	v_sub_f32_e32 v141, v141, v145
	v_sub_f32_e32 v142, v142, v146
	v_sub_f32_e32 v143, v143, v147
	v_add_u32_e32 v148, 1, v148
	v_subrev_u32_e32 v152, 8, v148
	v_max_i32_e32 v152, 0, v152
	v_add_u32_e32 v149, 8, v148
	v_min_u32_e32 v149, 0x1000, v149
	v_sub_u32_e32 v149, v149, v152
	v_cvt_f32_i32_e32 v149, v149
	v_rcp_iflag_f32_e32 v149, v149
	v_lshlrev_b32_e32 v144, 16, v28
	v_and_b32_e32 v145, 0xffff0000, v28
	v_lshlrev_b32_e32 v146, 16, v29
	v_and_b32_e32 v147, 0xffff0000, v29
	v_fma_f32 v144, v149, v140, -v144
	v_fma_f32 v145, v149, v141, -v145
	v_fma_f32 v146, v149, v142, -v146
	v_fma_f32 v147, v149, v143, -v147
	v_cvt_pk_bf16_f32 v154, v144, v145
	v_cvt_pk_bf16_f32 v155, v146, v147
	ds_write_b64 v151, v[154:155] offset:38496
	v_lshlrev_b32_e32 v144, 16, v226
	v_and_b32_e32 v145, 0xffff0000, v226
	v_lshlrev_b32_e32 v146, 16, v227
	v_and_b32_e32 v147, 0xffff0000, v227
	v_add_f32_e32 v140, v140, v144
	v_add_f32_e32 v141, v141, v145
	v_add_f32_e32 v142, v142, v146
	v_add_f32_e32 v143, v143, v147
	v_lshlrev_b32_e32 v144, 16, v12
	v_and_b32_e32 v145, 0xffff0000, v12
	v_lshlrev_b32_e32 v146, 16, v13
	v_and_b32_e32 v147, 0xffff0000, v13
	v_sub_f32_e32 v140, v140, v144
	v_sub_f32_e32 v141, v141, v145
	v_sub_f32_e32 v142, v142, v146
	v_sub_f32_e32 v143, v143, v147
	v_add_u32_e32 v148, 1, v148
	v_subrev_u32_e32 v152, 8, v148
	v_max_i32_e32 v152, 0, v152
	v_add_u32_e32 v149, 8, v148
	v_min_u32_e32 v149, 0x1000, v149
	v_sub_u32_e32 v149, v149, v152
	v_cvt_f32_i32_e32 v149, v149
	v_rcp_iflag_f32_e32 v149, v149
	v_lshlrev_b32_e32 v144, 16, v30
	v_and_b32_e32 v145, 0xffff0000, v30
	v_lshlrev_b32_e32 v146, 16, v31
	v_and_b32_e32 v147, 0xffff0000, v31
	v_fma_f32 v144, v149, v140, -v144
	v_fma_f32 v145, v149, v141, -v145
	v_fma_f32 v146, v149, v142, -v146
	v_fma_f32 v147, v149, v143, -v147
	v_cvt_pk_bf16_f32 v154, v144, v145
	v_cvt_pk_bf16_f32 v155, v146, v147
	ds_write_b64 v151, v[154:155] offset:38768
	s_branch .Lpw_done
.Lpw_2:
	ds_read_b64 v[8:9], v150 offset:1024
	ds_read_b64 v[10:11], v150 offset:1280
	ds_read_b64 v[12:13], v150 offset:1536
	ds_read_b64 v[14:15], v150 offset:1792
	ds_read_b64 v[16:17], v150 offset:2048
	ds_read_b64 v[18:19], v150 offset:2304
	ds_read_b64 v[20:21], v150 offset:2560
	ds_read_b64 v[22:23], v150 offset:2816
	ds_read_b64 v[24:25], v150 offset:3072
	ds_read_b64 v[26:27], v150 offset:3328
	ds_read_b64 v[28:29], v150 offset:3584
	ds_read_b64 v[30:31], v150 offset:3840
	ds_read_b64 v[214:215], v150 offset:4096
	ds_read_b64 v[216:217], v150 offset:4352
	ds_read_b64 v[218:219], v150 offset:4608
	ds_read_b64 v[220:221], v150 offset:4864
	s_waitcnt lgkmcnt(0)
	v_lshlrev_b32_e32 v140, 16, v8
	v_and_b32_e32 v141, 0xffff0000, v8
	v_lshlrev_b32_e32 v142, 16, v9
	v_and_b32_e32 v143, 0xffff0000, v9
	v_lshlrev_b32_e32 v144, 16, v10
	v_and_b32_e32 v145, 0xffff0000, v10
	v_lshlrev_b32_e32 v146, 16, v11
	v_and_b32_e32 v147, 0xffff0000, v11
	v_add_f32_e32 v140, v140, v144
	v_add_f32_e32 v141, v141, v145
	v_add_f32_e32 v142, v142, v146
	v_add_f32_e32 v143, v143, v147
	v_lshlrev_b32_e32 v144, 16, v12
	v_and_b32_e32 v145, 0xffff0000, v12
	v_lshlrev_b32_e32 v146, 16, v13
	v_and_b32_e32 v147, 0xffff0000, v13
	v_add_f32_e32 v140, v140, v144
	v_add_f32_e32 v141, v141, v145
	v_add_f32_e32 v142, v142, v146
	v_add_f32_e32 v143, v143, v147
	v_lshlrev_b32_e32 v144, 16, v14
	v_and_b32_e32 v145, 0xffff0000, v14
	v_lshlrev_b32_e32 v146, 16, v15
	v_and_b32_e32 v147, 0xffff0000, v15
	v_add_f32_e32 v140, v140, v144
	v_add_f32_e32 v141, v141, v145
	v_add_f32_e32 v142, v142, v146
	v_add_f32_e32 v143, v143, v147
	v_lshlrev_b32_e32 v144, 16, v16
	v_and_b32_e32 v145, 0xffff0000, v16
	v_lshlrev_b32_e32 v146, 16, v17
	v_and_b32_e32 v147, 0xffff0000, v17
	v_add_f32_e32 v140, v140, v144
	v_add_f32_e32 v141, v141, v145
	v_add_f32_e32 v142, v142, v146
	v_add_f32_e32 v143, v143, v147
	v_lshlrev_b32_e32 v144, 16, v18
	v_and_b32_e32 v145, 0xffff0000, v18
	v_lshlrev_b32_e32 v146, 16, v19
	v_and_b32_e32 v147, 0xffff0000, v19
	v_add_f32_e32 v140, v140, v144
	v_add_f32_e32 v141, v141, v145
	v_add_f32_e32 v142, v142, v146
	v_add_f32_e32 v143, v143, v147
	v_lshlrev_b32_e32 v144, 16, v20
	v_and_b32_e32 v145, 0xffff0000, v20
	v_lshlrev_b32_e32 v146, 16, v21
; __device__ __forceinline__ float bf2f(bf16_t v) { return __uint_as_float((unsigned)v << 16); }
; __device__ __forceinline__ unsigned cvtpk(float lo, float hi) { f32x2_t v = {lo, hi}; bf16x2_t b = __builtin_convertvector(v, bf16x2_t); return __builtin_bit_cast(unsigned, b); }
; #define LAS __attribute__((address_space(3)))
; __device__ __forceinline__ void pool_units(const Ptrs& P, LAS unsigned char* lds, int bx, int G, int tid, int wave, int lane) {
;     ...
;         {
;             const int c = tid & 127, tl0 = (tid >> 7) * 32, w2 = 1 << g; const LAS bf16_t* U = (const LAS bf16_t*)(lds + PL_U) + c; float sum = 0.f;
;             for (int j = tl0 - w2; j < tl0 + w2; ++j) sum += bf2f(U[(j + 8) * 128]);
;             for (int tl = tl0; tl < tl0 + 32; ++tl) {
;                 const int ts = ts0 + tl, lo = ts - w2 < 0 ? 0 : ts - w2, hi = ts + w2 > SEQ ? SEQ : ts + w2;
;                 const float d = sum * __builtin_amdgcn_rcpf((float)(hi - lo)) - bf2f(U[(tl + 8) * 128]);
;                 *(LAS bf16_t*)(lds + PL_A + tl * PL_AP + c * 2) = (bf16_t)(cvtpk(d, 0.f) & 0xffffu);
;                 sum += bf2f(U[(tl + w2 + 8) * 128]) - bf2f(U[(tl - w2 + 8) * 128]);
;             }
;         }
	v_and_b32_e32 v147, 0xffff0000, v21
	v_add_f32_e32 v140, v140, v144
	v_add_f32_e32 v141, v141, v145
	v_add_f32_e32 v142, v142, v146
	v_add_f32_e32 v143, v143, v147
	v_lshlrev_b32_e32 v144, 16, v22
	v_and_b32_e32 v145, 0xffff0000, v22
	v_lshlrev_b32_e32 v146, 16, v23
	v_and_b32_e32 v147, 0xffff0000, v23
	v_add_f32_e32 v140, v140, v144
	v_add_f32_e32 v141, v141, v145
	v_add_f32_e32 v142, v142, v146
	v_add_f32_e32 v143, v143, v147
	v_subrev_u32_e32 v152, 4, v148
	v_max_i32_e32 v152, 0, v152
	v_add_u32_e32 v149, 4, v148
	v_min_u32_e32 v149, 0x1000, v149
	v_sub_u32_e32 v149, v149, v152
	v_cvt_f32_i32_e32 v149, v149
	v_rcp_iflag_f32_e32 v149, v149
	v_lshlrev_b32_e32 v144, 16, v16
	v_and_b32_e32 v145, 0xffff0000, v16
	v_lshlrev_b32_e32 v146, 16, v17
	v_and_b32_e32 v147, 0xffff0000, v17
	v_fma_f32 v144, v149, v140, -v144
	v_fma_f32 v145, v149, v141, -v145
	v_fma_f32 v146, v149, v142, -v146
	v_fma_f32 v147, v149, v143, -v147
	v_cvt_pk_bf16_f32 v154, v144, v145
	v_cvt_pk_bf16_f32 v155, v146, v147
	ds_write_b64 v151, v[154:155] offset:36864
	v_lshlrev_b32_e32 v144, 16, v24
	v_and_b32_e32 v145, 0xffff0000, v24
	v_lshlrev_b32_e32 v146, 16, v25
	v_and_b32_e32 v147, 0xffff0000, v25
	v_add_f32_e32 v140, v140, v144
	v_add_f32_e32 v141, v141, v145
	v_add_f32_e32 v142, v142, v146
	v_add_f32_e32 v143, v143, v147
	v_lshlrev_b32_e32 v144, 16, v8
	v_and_b32_e32 v145, 0xffff0000, v8
	v_lshlrev_b32_e32 v146, 16, v9
	v_and_b32_e32 v147, 0xffff0000, v9
	v_sub_f32_e32 v140, v140, v144
	v_sub_f32_e32 v141, v141, v145
	v_sub_f32_e32 v142, v142, v146
	v_sub_f32_e32 v143, v143, v147
	v_add_u32_e32 v148, 1, v148
	v_subrev_u32_e32 v152, 4, v148
	v_max_i32_e32 v152, 0, v152
	v_add_u32_e32 v149, 4, v148
	v_min_u32_e32 v149, 0x1000, v149
	v_sub_u32_e32 v149, v149, v152
	v_cvt_f32_i32_e32 v149, v149
	v_rcp_iflag_f32_e32 v149, v149
	v_lshlrev_b32_e32 v144, 16, v18
	v_and_b32_e32 v145, 0xffff0000, v18
	v_lshlrev_b32_e32 v146, 16, v19
	v_and_b32_e32 v147, 0xffff0000, v19
	v_fma_f32 v144, v149, v140, -v144
	v_fma_f32 v145, v149, v141, -v145
	v_fma_f32 v146, v149, v142, -v146
	v_fma_f32 v147, v149, v143, -v147
	v_cvt_pk_bf16_f32 v154, v144, v145
	v_cvt_pk_bf16_f32 v155, v146, v147
	ds_write_b64 v151, v[154:155] offset:37136
	v_lshlrev_b32_e32 v144, 16, v26
	v_and_b32_e32 v145, 0xffff0000, v26
	v_lshlrev_b32_e32 v146, 16, v27
	v_and_b32_e32 v147, 0xffff0000, v27
	v_add_f32_e32 v140, v140, v144
	v_add_f32_e32 v141, v141, v145
	v_add_f32_e32 v142, v142, v146
	v_add_f32_e32 v143, v143, v147
	v_lshlrev_b32_e32 v144, 16, v10
	v_and_b32_e32 v145, 0xffff0000, v10
	v_lshlrev_b32_e32 v146, 16, v11
	v_and_b32_e32 v147, 0xffff0000, v11
	v_sub_f32_e32 v140, v140, v144
	v_sub_f32_e32 v141, v141, v145
	v_sub_f32_e32 v142, v142, v146
	v_sub_f32_e32 v143, v143, v147
	v_add_u32_e32 v148, 1, v148
	v_subrev_u32_e32 v152, 4, v148
	v_max_i32_e32 v152, 0, v152
	v_add_u32_e32 v149, 4, v148
	v_min_u32_e32 v149, 0x1000, v149
	v_sub_u32_e32 v149, v149, v152
	v_cvt_f32_i32_e32 v149, v149
	v_rcp_iflag_f32_e32 v149, v149
	v_lshlrev_b32_e32 v144, 16, v20
	v_and_b32_e32 v145, 0xffff0000, v20
	v_lshlrev_b32_e32 v146, 16, v21
	v_and_b32_e32 v147, 0xffff0000, v21
	v_fma_f32 v144, v149, v140, -v144
	v_fma_f32 v145, v149, v141, -v145
	v_fma_f32 v146, v149, v142, -v146
	v_fma_f32 v147, v149, v143, -v147
	v_cvt_pk_bf16_f32 v154, v144, v145
	v_cvt_pk_bf16_f32 v155, v146, v147
	ds_write_b64 v151, v[154:155] offset:37408
	v_lshlrev_b32_e32 v144, 16, v28
	v_and_b32_e32 v145, 0xffff0000, v28
	v_lshlrev_b32_e32 v146, 16, v29
	v_and_b32_e32 v147, 0xffff0000, v29
	v_add_f32_e32 v140, v140, v144
	v_add_f32_e32 v141, v141, v145
	v_add_f32_e32 v142, v142, v146
	v_add_f32_e32 v143, v143, v147
	v_lshlrev_b32_e32 v144, 16, v12
	v_and_b32_e32 v145, 0xffff0000, v12
	v_lshlrev_b32_e32 v146, 16, v13
	v_and_b32_e32 v147, 0xffff0000, v13
	v_sub_f32_e32 v140, v140, v144
	v_sub_f32_e32 v141, v141, v145
	v_sub_f32_e32 v142, v142, v146
	v_sub_f32_e32 v143, v143, v147
	v_add_u32_e32 v148, 1, v148
	v_subrev_u32_e32 v152, 4, v148
	v_max_i32_e32 v152, 0, v152
	v_add_u32_e32 v149, 4, v148
	v_min_u32_e32 v149, 0x1000, v149
	v_sub_u32_e32 v149, v149, v152
	v_cvt_f32_i32_e32 v149, v149
	v_rcp_iflag_f32_e32 v149, v149
	v_lshlrev_b32_e32 v144, 16, v22
	v_and_b32_e32 v145, 0xffff0000, v22
	v_lshlrev_b32_e32 v146, 16, v23
	v_and_b32_e32 v147, 0xffff0000, v23
	v_fma_f32 v144, v149, v140, -v144
	v_fma_f32 v145, v149, v141, -v145
	v_fma_f32 v146, v149, v142, -v146
	v_fma_f32 v147, v149, v143, -v147
	v_cvt_pk_bf16_f32 v154, v144, v145
	v_cvt_pk_bf16_f32 v155, v146, v147
	ds_write_b64 v151, v[154:155] offset:37680
	v_lshlrev_b32_e32 v144, 16, v30
	v_and_b32_e32 v145, 0xffff0000, v30
	v_lshlrev_b32_e32 v146, 16, v31
	v_and_b32_e32 v147, 0xffff0000, v31
	v_add_f32_e32 v140, v140, v144
	v_add_f32_e32 v141, v141, v145
	v_add_f32_e32 v142, v142, v146
	v_add_f32_e32 v143, v143, v147
	v_lshlrev_b32_e32 v144, 16, v14
	v_and_b32_e32 v145, 0xffff0000, v14
	v_lshlrev_b32_e32 v146, 16, v15
	v_and_b32_e32 v147, 0xffff0000, v15
	v_sub_f32_e32 v140, v140, v144
	v_sub_f32_e32 v141, v141, v145
	v_sub_f32_e32 v142, v142, v146
	v_sub_f32_e32 v143, v143, v147
	v_add_u32_e32 v148, 1, v148
	v_subrev_u32_e32 v152, 4, v148
	v_max_i32_e32 v152, 0, v152
	v_add_u32_e32 v149, 4, v148
	v_min_u32_e32 v149, 0x1000, v149
	v_sub_u32_e32 v149, v149, v152
	v_cvt_f32_i32_e32 v149, v149
	v_rcp_iflag_f32_e32 v149, v149
	v_lshlrev_b32_e32 v144, 16, v24
	v_and_b32_e32 v145, 0xffff0000, v24
	v_lshlrev_b32_e32 v146, 16, v25
	v_and_b32_e32 v147, 0xffff0000, v25
	v_fma_f32 v144, v149, v140, -v144
	v_fma_f32 v145, v149, v141, -v145
	v_fma_f32 v146, v149, v142, -v146
	v_fma_f32 v147, v149, v143, -v147
; __device__ __forceinline__ float bf2f(bf16_t v) { return __uint_as_float((unsigned)v << 16); }
; __device__ __forceinline__ unsigned cvtpk(float lo, float hi) { f32x2_t v = {lo, hi}; bf16x2_t b = __builtin_convertvector(v, bf16x2_t); return __builtin_bit_cast(unsigned, b); }
; #define LAS __attribute__((address_space(3)))
; __device__ __forceinline__ void pool_units(const Ptrs& P, LAS unsigned char* lds, int bx, int G, int tid, int wave, int lane) {
;     ...
;         {
;             const int c = tid & 127, tl0 = (tid >> 7) * 32, w2 = 1 << g; const LAS bf16_t* U = (const LAS bf16_t*)(lds + PL_U) + c; float sum = 0.f;
;             for (int j = tl0 - w2; j < tl0 + w2; ++j) sum += bf2f(U[(j + 8) * 128]);
;             for (int tl = tl0; tl < tl0 + 32; ++tl) {
;                 const int ts = ts0 + tl, lo = ts - w2 < 0 ? 0 : ts - w2, hi = ts + w2 > SEQ ? SEQ : ts + w2;
;                 const float d = sum * __builtin_amdgcn_rcpf((float)(hi - lo)) - bf2f(U[(tl + 8) * 128]);
;                 *(LAS bf16_t*)(lds + PL_A + tl * PL_AP + c * 2) = (bf16_t)(cvtpk(d, 0.f) & 0xffffu);
;                 sum += bf2f(U[(tl + w2 + 8) * 128]) - bf2f(U[(tl - w2 + 8) * 128]);
;             }
;         }
	v_cvt_pk_bf16_f32 v154, v144, v145
	v_cvt_pk_bf16_f32 v155, v146, v147
	ds_write_b64 v151, v[154:155] offset:37952
	v_lshlrev_b32_e32 v144, 16, v214
	v_and_b32_e32 v145, 0xffff0000, v214
	v_lshlrev_b32_e32 v146, 16, v215
	v_and_b32_e32 v147, 0xffff0000, v215
	v_add_f32_e32 v140, v140, v144
	v_add_f32_e32 v141, v141, v145
	v_add_f32_e32 v142, v142, v146
	v_add_f32_e32 v143, v143, v147
	v_lshlrev_b32_e32 v144, 16, v16
	v_and_b32_e32 v145, 0xffff0000, v16
	v_lshlrev_b32_e32 v146, 16, v17
	v_and_b32_e32 v147, 0xffff0000, v17
	v_sub_f32_e32 v140, v140, v144
	v_sub_f32_e32 v141, v141, v145
	v_sub_f32_e32 v142, v142, v146
	v_sub_f32_e32 v143, v143, v147
	v_add_u32_e32 v148, 1, v148
	v_subrev_u32_e32 v152, 4, v148
	v_max_i32_e32 v152, 0, v152
	v_add_u32_e32 v149, 4, v148
	v_min_u32_e32 v149, 0x1000, v149
	v_sub_u32_e32 v149, v149, v152
	v_cvt_f32_i32_e32 v149, v149
	v_rcp_iflag_f32_e32 v149, v149
	v_lshlrev_b32_e32 v144, 16, v26
	v_and_b32_e32 v145, 0xffff0000, v26
	v_lshlrev_b32_e32 v146, 16, v27
	v_and_b32_e32 v147, 0xffff0000, v27
	v_fma_f32 v144, v149, v140, -v144
	v_fma_f32 v145, v149, v141, -v145
	v_fma_f32 v146, v149, v142, -v146
	v_fma_f32 v147, v149, v143, -v147
	v_cvt_pk_bf16_f32 v154, v144, v145
	v_cvt_pk_bf16_f32 v155, v146, v147
	ds_write_b64 v151, v[154:155] offset:38224
	v_lshlrev_b32_e32 v144, 16, v216
	v_and_b32_e32 v145, 0xffff0000, v216
	v_lshlrev_b32_e32 v146, 16, v217
	v_and_b32_e32 v147, 0xffff0000, v217
	v_add_f32_e32 v140, v140, v144
	v_add_f32_e32 v141, v141, v145
	v_add_f32_e32 v142, v142, v146
	v_add_f32_e32 v143, v143, v147
	v_lshlrev_b32_e32 v144, 16, v18
	v_and_b32_e32 v145, 0xffff0000, v18
	v_lshlrev_b32_e32 v146, 16, v19
	v_and_b32_e32 v147, 0xffff0000, v19
	v_sub_f32_e32 v140, v140, v144
	v_sub_f32_e32 v141, v141, v145
	v_sub_f32_e32 v142, v142, v146
	v_sub_f32_e32 v143, v143, v147
	v_add_u32_e32 v148, 1, v148
	v_subrev_u32_e32 v152, 4, v148
	v_max_i32_e32 v152, 0, v152
	v_add_u32_e32 v149, 4, v148
	v_min_u32_e32 v149, 0x1000, v149
	v_sub_u32_e32 v149, v149, v152
	v_cvt_f32_i32_e32 v149, v149
	v_rcp_iflag_f32_e32 v149, v149
	v_lshlrev_b32_e32 v144, 16, v28
	v_and_b32_e32 v145, 0xffff0000, v28
	v_lshlrev_b32_e32 v146, 16, v29
	v_and_b32_e32 v147, 0xffff0000, v29
	v_fma_f32 v144, v149, v140, -v144
	v_fma_f32 v145, v149, v141, -v145
	v_fma_f32 v146, v149, v142, -v146
	v_fma_f32 v147, v149, v143, -v147
	v_cvt_pk_bf16_f32 v154, v144, v145
	v_cvt_pk_bf16_f32 v155, v146, v147
	ds_write_b64 v151, v[154:155] offset:38496
	v_lshlrev_b32_e32 v144, 16, v218
	v_and_b32_e32 v145, 0xffff0000, v218
	v_lshlrev_b32_e32 v146, 16, v219
	v_and_b32_e32 v147, 0xffff0000, v219
	v_add_f32_e32 v140, v140, v144
	v_add_f32_e32 v141, v141, v145
	v_add_f32_e32 v142, v142, v146
	v_add_f32_e32 v143, v143, v147
	v_lshlrev_b32_e32 v144, 16, v20
	v_and_b32_e32 v145, 0xffff0000, v20
	v_lshlrev_b32_e32 v146, 16, v21
	v_and_b32_e32 v147, 0xffff0000, v21
	v_sub_f32_e32 v140, v140, v144
	v_sub_f32_e32 v141, v141, v145
	v_sub_f32_e32 v142, v142, v146
	v_sub_f32_e32 v143, v143, v147
	v_add_u32_e32 v148, 1, v148
	v_subrev_u32_e32 v152, 4, v148
	v_max_i32_e32 v152, 0, v152
	v_add_u32_e32 v149, 4, v148
	v_min_u32_e32 v149, 0x1000, v149
	v_sub_u32_e32 v149, v149, v152
	v_cvt_f32_i32_e32 v149, v149
	v_rcp_iflag_f32_e32 v149, v149
	v_lshlrev_b32_e32 v144, 16, v30
	v_and_b32_e32 v145, 0xffff0000, v30
	v_lshlrev_b32_e32 v146, 16, v31
	v_and_b32_e32 v147, 0xffff0000, v31
	v_fma_f32 v144, v149, v140, -v144
	v_fma_f32 v145, v149, v141, -v145
	v_fma_f32 v146, v149, v142, -v146
	v_fma_f32 v147, v149, v143, -v147
	v_cvt_pk_bf16_f32 v154, v144, v145
	v_cvt_pk_bf16_f32 v155, v146, v147
	ds_write_b64 v151, v[154:155] offset:38768
	s_branch .Lpw_done
.Lpw_1:
	ds_read_b64 v[12:13], v150 offset:1536
	ds_read_b64 v[14:15], v150 offset:1792
	ds_read_b64 v[16:17], v150 offset:2048
	ds_read_b64 v[18:19], v150 offset:2304
	ds_read_b64 v[20:21], v150 offset:2560
	ds_read_b64 v[22:23], v150 offset:2816
	ds_read_b64 v[24:25], v150 offset:3072
	ds_read_b64 v[26:27], v150 offset:3328
	ds_read_b64 v[28:29], v150 offset:3584
	ds_read_b64 v[30:31], v150 offset:3840
	ds_read_b64 v[214:215], v150 offset:4096
	ds_read_b64 v[216:217], v150 offset:4352
	s_waitcnt lgkmcnt(0)
	v_lshlrev_b32_e32 v140, 16, v12
	v_and_b32_e32 v141, 0xffff0000, v12
	v_lshlrev_b32_e32 v142, 16, v13
	v_and_b32_e32 v143, 0xffff0000, v13
	v_lshlrev_b32_e32 v144, 16, v14
	v_and_b32_e32 v145, 0xffff0000, v14
	v_lshlrev_b32_e32 v146, 16, v15
	v_and_b32_e32 v147, 0xffff0000, v15
	v_add_f32_e32 v140, v140, v144
	v_add_f32_e32 v141, v141, v145
	v_add_f32_e32 v142, v142, v146
	v_add_f32_e32 v143, v143, v147
	v_lshlrev_b32_e32 v144, 16, v16
	v_and_b32_e32 v145, 0xffff0000, v16
	v_lshlrev_b32_e32 v146, 16, v17
	v_and_b32_e32 v147, 0xffff0000, v17
	v_add_f32_e32 v140, v140, v144
	v_add_f32_e32 v141, v141, v145
	v_add_f32_e32 v142, v142, v146
	v_add_f32_e32 v143, v143, v147
	v_lshlrev_b32_e32 v144, 16, v18
	v_and_b32_e32 v145, 0xffff0000, v18
	v_lshlrev_b32_e32 v146, 16, v19
	v_and_b32_e32 v147, 0xffff0000, v19
	v_add_f32_e32 v140, v140, v144
	v_add_f32_e32 v141, v141, v145
	v_add_f32_e32 v142, v142, v146
	v_add_f32_e32 v143, v143, v147
	v_subrev_u32_e32 v152, 2, v148
	v_max_i32_e32 v152, 0, v152
	v_add_u32_e32 v149, 2, v148
	v_min_u32_e32 v149, 0x1000, v149
	v_sub_u32_e32 v149, v149, v152
	v_cvt_f32_i32_e32 v149, v149
	v_rcp_iflag_f32_e32 v149, v149
	v_lshlrev_b32_e32 v144, 16, v16
	v_and_b32_e32 v145, 0xffff0000, v16
	v_lshlrev_b32_e32 v146, 16, v17
	v_and_b32_e32 v147, 0xffff0000, v17
	v_fma_f32 v144, v149, v140, -v144
	v_fma_f32 v145, v149, v141, -v145
	v_fma_f32 v146, v149, v142, -v146
	v_fma_f32 v147, v149, v143, -v147
; __device__ __forceinline__ float bf2f(bf16_t v) { return __uint_as_float((unsigned)v << 16); }
; __device__ __forceinline__ unsigned cvtpk(float lo, float hi) { f32x2_t v = {lo, hi}; bf16x2_t b = __builtin_convertvector(v, bf16x2_t); return __builtin_bit_cast(unsigned, b); }
; #define LAS __attribute__((address_space(3)))
; __device__ __forceinline__ void pool_units(const Ptrs& P, LAS unsigned char* lds, int bx, int G, int tid, int wave, int lane) {
;     ...
;         {
;             const int c = tid & 127, tl0 = (tid >> 7) * 32, w2 = 1 << g; const LAS bf16_t* U = (const LAS bf16_t*)(lds + PL_U) + c; float sum = 0.f;
;             for (int j = tl0 - w2; j < tl0 + w2; ++j) sum += bf2f(U[(j + 8) * 128]);
;             for (int tl = tl0; tl < tl0 + 32; ++tl) {
;                 const int ts = ts0 + tl, lo = ts - w2 < 0 ? 0 : ts - w2, hi = ts + w2 > SEQ ? SEQ : ts + w2;
;                 const float d = sum * __builtin_amdgcn_rcpf((float)(hi - lo)) - bf2f(U[(tl + 8) * 128]);
;                 *(LAS bf16_t*)(lds + PL_A + tl * PL_AP + c * 2) = (bf16_t)(cvtpk(d, 0.f) & 0xffffu);
;                 sum += bf2f(U[(tl + w2 + 8) * 128]) - bf2f(U[(tl - w2 + 8) * 128]);
;             }
;         }
	v_cvt_pk_bf16_f32 v154, v144, v145
	v_cvt_pk_bf16_f32 v155, v146, v147
	ds_write_b64 v151, v[154:155] offset:36864
	v_lshlrev_b32_e32 v144, 16, v20
	v_and_b32_e32 v145, 0xffff0000, v20
	v_lshlrev_b32_e32 v146, 16, v21
	v_and_b32_e32 v147, 0xffff0000, v21
	v_add_f32_e32 v140, v140, v144
	v_add_f32_e32 v141, v141, v145
	v_add_f32_e32 v142, v142, v146
	v_add_f32_e32 v143, v143, v147
	v_lshlrev_b32_e32 v144, 16, v12
	v_and_b32_e32 v145, 0xffff0000, v12
	v_lshlrev_b32_e32 v146, 16, v13
	v_and_b32_e32 v147, 0xffff0000, v13
	v_sub_f32_e32 v140, v140, v144
	v_sub_f32_e32 v141, v141, v145
	v_sub_f32_e32 v142, v142, v146
	v_sub_f32_e32 v143, v143, v147
	v_add_u32_e32 v148, 1, v148
	v_subrev_u32_e32 v152, 2, v148
	v_max_i32_e32 v152, 0, v152
	v_add_u32_e32 v149, 2, v148
	v_min_u32_e32 v149, 0x1000, v149
	v_sub_u32_e32 v149, v149, v152
	v_cvt_f32_i32_e32 v149, v149
	v_rcp_iflag_f32_e32 v149, v149
	v_lshlrev_b32_e32 v144, 16, v18
	v_and_b32_e32 v145, 0xffff0000, v18
	v_lshlrev_b32_e32 v146, 16, v19
	v_and_b32_e32 v147, 0xffff0000, v19
	v_fma_f32 v144, v149, v140, -v144
	v_fma_f32 v145, v149, v141, -v145
	v_fma_f32 v146, v149, v142, -v146
	v_fma_f32 v147, v149, v143, -v147
	v_cvt_pk_bf16_f32 v154, v144, v145
	v_cvt_pk_bf16_f32 v155, v146, v147
	ds_write_b64 v151, v[154:155] offset:37136
	v_lshlrev_b32_e32 v144, 16, v22
	v_and_b32_e32 v145, 0xffff0000, v22
	v_lshlrev_b32_e32 v146, 16, v23
	v_and_b32_e32 v147, 0xffff0000, v23
	v_add_f32_e32 v140, v140, v144
	v_add_f32_e32 v141, v141, v145
	v_add_f32_e32 v142, v142, v146
	v_add_f32_e32 v143, v143, v147
	v_lshlrev_b32_e32 v144, 16, v14
	v_and_b32_e32 v145, 0xffff0000, v14
	v_lshlrev_b32_e32 v146, 16, v15
	v_and_b32_e32 v147, 0xffff0000, v15
	v_sub_f32_e32 v140, v140, v144
	v_sub_f32_e32 v141, v141, v145
	v_sub_f32_e32 v142, v142, v146
	v_sub_f32_e32 v143, v143, v147
	v_add_u32_e32 v148, 1, v148
	v_subrev_u32_e32 v152, 2, v148
	v_max_i32_e32 v152, 0, v152
	v_add_u32_e32 v149, 2, v148
	v_min_u32_e32 v149, 0x1000, v149
	v_sub_u32_e32 v149, v149, v152
	v_cvt_f32_i32_e32 v149, v149
	v_rcp_iflag_f32_e32 v149, v149
	v_lshlrev_b32_e32 v144, 16, v20
	v_and_b32_e32 v145, 0xffff0000, v20
	v_lshlrev_b32_e32 v146, 16, v21
	v_and_b32_e32 v147, 0xffff0000, v21
	v_fma_f32 v144, v149, v140, -v144
	v_fma_f32 v145, v149, v141, -v145
	v_fma_f32 v146, v149, v142, -v146
	v_fma_f32 v147, v149, v143, -v147
	v_cvt_pk_bf16_f32 v154, v144, v145
	v_cvt_pk_bf16_f32 v155, v146, v147
	ds_write_b64 v151, v[154:155] offset:37408
	v_lshlrev_b32_e32 v144, 16, v24
	v_and_b32_e32 v145, 0xffff0000, v24
	v_lshlrev_b32_e32 v146, 16, v25
	v_and_b32_e32 v147, 0xffff0000, v25
	v_add_f32_e32 v140, v140, v144
	v_add_f32_e32 v141, v141, v145
	v_add_f32_e32 v142, v142, v146
	v_add_f32_e32 v143, v143, v147
	v_lshlrev_b32_e32 v144, 16, v16
	v_and_b32_e32 v145, 0xffff0000, v16
	v_lshlrev_b32_e32 v146, 16, v17
	v_and_b32_e32 v147, 0xffff0000, v17
	v_sub_f32_e32 v140, v140, v144
	v_sub_f32_e32 v141, v141, v145
	v_sub_f32_e32 v142, v142, v146
	v_sub_f32_e32 v143, v143, v147
	v_add_u32_e32 v148, 1, v148
	v_subrev_u32_e32 v152, 2, v148
	v_max_i32_e32 v152, 0, v152
	v_add_u32_e32 v149, 2, v148
	v_min_u32_e32 v149, 0x1000, v149
	v_sub_u32_e32 v149, v149, v152
	v_cvt_f32_i32_e32 v149, v149
	v_rcp_iflag_f32_e32 v149, v149
	v_lshlrev_b32_e32 v144, 16, v22
	v_and_b32_e32 v145, 0xffff0000, v22
	v_lshlrev_b32_e32 v146, 16, v23
	v_and_b32_e32 v147, 0xffff0000, v23
	v_fma_f32 v144, v149, v140, -v144
	v_fma_f32 v145, v149, v141, -v145
	v_fma_f32 v146, v149, v142, -v146
	v_fma_f32 v147, v149, v143, -v147
	v_cvt_pk_bf16_f32 v154, v144, v145
	v_cvt_pk_bf16_f32 v155, v146, v147
	ds_write_b64 v151, v[154:155] offset:37680
	v_lshlrev_b32_e32 v144, 16, v26
	v_and_b32_e32 v145, 0xffff0000, v26
	v_lshlrev_b32_e32 v146, 16, v27
	v_and_b32_e32 v147, 0xffff0000, v27
	v_add_f32_e32 v140, v140, v144
	v_add_f32_e32 v141, v141, v145
	v_add_f32_e32 v142, v142, v146
	v_add_f32_e32 v143, v143, v147
	v_lshlrev_b32_e32 v144, 16, v18
	v_and_b32_e32 v145, 0xffff0000, v18
	v_lshlrev_b32_e32 v146, 16, v19
	v_and_b32_e32 v147, 0xffff0000, v19
	v_sub_f32_e32 v140, v140, v144
	v_sub_f32_e32 v141, v141, v145
	v_sub_f32_e32 v142, v142, v146
	v_sub_f32_e32 v143, v143, v147
	v_add_u32_e32 v148, 1, v148
	v_subrev_u32_e32 v152, 2, v148
	v_max_i32_e32 v152, 0, v152
	v_add_u32_e32 v149, 2, v148
	v_min_u32_e32 v149, 0x1000, v149
	v_sub_u32_e32 v149, v149, v152
	v_cvt_f32_i32_e32 v149, v149
	v_rcp_iflag_f32_e32 v149, v149
	v_lshlrev_b32_e32 v144, 16, v24
	v_and_b32_e32 v145, 0xffff0000, v24
	v_lshlrev_b32_e32 v146, 16, v25
	v_and_b32_e32 v147, 0xffff0000, v25
	v_fma_f32 v144, v149, v140, -v144
	v_fma_f32 v145, v149, v141, -v145
	v_fma_f32 v146, v149, v142, -v146
	v_fma_f32 v147, v149, v143, -v147
	v_cvt_pk_bf16_f32 v154, v144, v145
	v_cvt_pk_bf16_f32 v155, v146, v147
	ds_write_b64 v151, v[154:155] offset:37952
	v_lshlrev_b32_e32 v144, 16, v28
	v_and_b32_e32 v145, 0xffff0000, v28
	v_lshlrev_b32_e32 v146, 16, v29
	v_and_b32_e32 v147, 0xffff0000, v29
	v_add_f32_e32 v140, v140, v144
	v_add_f32_e32 v141, v141, v145
	v_add_f32_e32 v142, v142, v146
	v_add_f32_e32 v143, v143, v147
	v_lshlrev_b32_e32 v144, 16, v20
	v_and_b32_e32 v145, 0xffff0000, v20
	v_lshlrev_b32_e32 v146, 16, v21
	v_and_b32_e32 v147, 0xffff0000, v21
	v_sub_f32_e32 v140, v140, v144
	v_sub_f32_e32 v141, v141, v145
	v_sub_f32_e32 v142, v142, v146
	v_sub_f32_e32 v143, v143, v147
	v_add_u32_e32 v148, 1, v148
	v_subrev_u32_e32 v152, 2, v148
	v_max_i32_e32 v152, 0, v152
	v_add_u32_e32 v149, 2, v148
	v_min_u32_e32 v149, 0x1000, v149
	v_sub_u32_e32 v149, v149, v152
	v_cvt_f32_i32_e32 v149, v149
	v_rcp_iflag_f32_e32 v149, v149
	v_lshlrev_b32_e32 v144, 16, v26
; __device__ __forceinline__ float bf2f(bf16_t v) { return __uint_as_float((unsigned)v << 16); }
; __device__ __forceinline__ unsigned cvtpk(float lo, float hi) { f32x2_t v = {lo, hi}; bf16x2_t b = __builtin_convertvector(v, bf16x2_t); return __builtin_bit_cast(unsigned, b); }
; #define LAS __attribute__((address_space(3)))
; __device__ __forceinline__ void pool_units(const Ptrs& P, LAS unsigned char* lds, int bx, int G, int tid, int wave, int lane) {
;     ...
;         {
;             const int c = tid & 127, tl0 = (tid >> 7) * 32, w2 = 1 << g; const LAS bf16_t* U = (const LAS bf16_t*)(lds + PL_U) + c; float sum = 0.f;
;             for (int j = tl0 - w2; j < tl0 + w2; ++j) sum += bf2f(U[(j + 8) * 128]);
;             for (int tl = tl0; tl < tl0 + 32; ++tl) {
;                 const int ts = ts0 + tl, lo = ts - w2 < 0 ? 0 : ts - w2, hi = ts + w2 > SEQ ? SEQ : ts + w2;
;                 const float d = sum * __builtin_amdgcn_rcpf((float)(hi - lo)) - bf2f(U[(tl + 8) * 128]);
;                 *(LAS bf16_t*)(lds + PL_A + tl * PL_AP + c * 2) = (bf16_t)(cvtpk(d, 0.f) & 0xffffu);
;                 sum += bf2f(U[(tl + w2 + 8) * 128]) - bf2f(U[(tl - w2 + 8) * 128]);
;             }
;         }
	v_and_b32_e32 v145, 0xffff0000, v26
	v_lshlrev_b32_e32 v146, 16, v27
	v_and_b32_e32 v147, 0xffff0000, v27
	v_fma_f32 v144, v149, v140, -v144
	v_fma_f32 v145, v149, v141, -v145
	v_fma_f32 v146, v149, v142, -v146
	v_fma_f32 v147, v149, v143, -v147
	v_cvt_pk_bf16_f32 v154, v144, v145
	v_cvt_pk_bf16_f32 v155, v146, v147
	ds_write_b64 v151, v[154:155] offset:38224
	v_lshlrev_b32_e32 v144, 16, v30
	v_and_b32_e32 v145, 0xffff0000, v30
	v_lshlrev_b32_e32 v146, 16, v31
	v_and_b32_e32 v147, 0xffff0000, v31
	v_add_f32_e32 v140, v140, v144
	v_add_f32_e32 v141, v141, v145
	v_add_f32_e32 v142, v142, v146
	v_add_f32_e32 v143, v143, v147
	v_lshlrev_b32_e32 v144, 16, v22
	v_and_b32_e32 v145, 0xffff0000, v22
	v_lshlrev_b32_e32 v146, 16, v23
	v_and_b32_e32 v147, 0xffff0000, v23
	v_sub_f32_e32 v140, v140, v144
	v_sub_f32_e32 v141, v141, v145
	v_sub_f32_e32 v142, v142, v146
	v_sub_f32_e32 v143, v143, v147
	v_add_u32_e32 v148, 1, v148
	v_subrev_u32_e32 v152, 2, v148
	v_max_i32_e32 v152, 0, v152
	v_add_u32_e32 v149, 2, v148
	v_min_u32_e32 v149, 0x1000, v149
	v_sub_u32_e32 v149, v149, v152
	v_cvt_f32_i32_e32 v149, v149
	v_rcp_iflag_f32_e32 v149, v149
	v_lshlrev_b32_e32 v144, 16, v28
	v_and_b32_e32 v145, 0xffff0000, v28
	v_lshlrev_b32_e32 v146, 16, v29
	v_and_b32_e32 v147, 0xffff0000, v29
	v_fma_f32 v144, v149, v140, -v144
	v_fma_f32 v145, v149, v141, -v145
	v_fma_f32 v146, v149, v142, -v146
	v_fma_f32 v147, v149, v143, -v147
	v_cvt_pk_bf16_f32 v154, v144, v145
	v_cvt_pk_bf16_f32 v155, v146, v147
	ds_write_b64 v151, v[154:155] offset:38496
	v_lshlrev_b32_e32 v144, 16, v214
	v_and_b32_e32 v145, 0xffff0000, v214
	v_lshlrev_b32_e32 v146, 16, v215
	v_and_b32_e32 v147, 0xffff0000, v215
	v_add_f32_e32 v140, v140, v144
	v_add_f32_e32 v141, v141, v145
	v_add_f32_e32 v142, v142, v146
	v_add_f32_e32 v143, v143, v147
	v_lshlrev_b32_e32 v144, 16, v24
	v_and_b32_e32 v145, 0xffff0000, v24
	v_lshlrev_b32_e32 v146, 16, v25
	v_and_b32_e32 v147, 0xffff0000, v25
	v_sub_f32_e32 v140, v140, v144
	v_sub_f32_e32 v141, v141, v145
	v_sub_f32_e32 v142, v142, v146
	v_sub_f32_e32 v143, v143, v147
	v_add_u32_e32 v148, 1, v148
	v_subrev_u32_e32 v152, 2, v148
	v_max_i32_e32 v152, 0, v152
	v_add_u32_e32 v149, 2, v148
	v_min_u32_e32 v149, 0x1000, v149
	v_sub_u32_e32 v149, v149, v152
	v_cvt_f32_i32_e32 v149, v149
	v_rcp_iflag_f32_e32 v149, v149
	v_lshlrev_b32_e32 v144, 16, v30
	v_and_b32_e32 v145, 0xffff0000, v30
	v_lshlrev_b32_e32 v146, 16, v31
	v_and_b32_e32 v147, 0xffff0000, v31
	v_fma_f32 v144, v149, v140, -v144
	v_fma_f32 v145, v149, v141, -v145
	v_fma_f32 v146, v149, v142, -v146
	v_fma_f32 v147, v149, v143, -v147
	v_cvt_pk_bf16_f32 v154, v144, v145
	v_cvt_pk_bf16_f32 v155, v146, v147
	ds_write_b64 v151, v[154:155] offset:38768
	s_branch .Lpw_done
.Lpw_0:
	ds_read_b64 v[14:15], v150 offset:1792
	ds_read_b64 v[16:17], v150 offset:2048
	ds_read_b64 v[18:19], v150 offset:2304
	ds_read_b64 v[20:21], v150 offset:2560
	ds_read_b64 v[22:23], v150 offset:2816
	ds_read_b64 v[24:25], v150 offset:3072
	ds_read_b64 v[26:27], v150 offset:3328
	ds_read_b64 v[28:29], v150 offset:3584
	ds_read_b64 v[30:31], v150 offset:3840
	ds_read_b64 v[214:215], v150 offset:4096
	s_waitcnt lgkmcnt(0)
	v_lshlrev_b32_e32 v140, 16, v14
	v_and_b32_e32 v141, 0xffff0000, v14
	v_lshlrev_b32_e32 v142, 16, v15
	v_and_b32_e32 v143, 0xffff0000, v15
	v_lshlrev_b32_e32 v144, 16, v16
	v_and_b32_e32 v145, 0xffff0000, v16
	v_lshlrev_b32_e32 v146, 16, v17
	v_and_b32_e32 v147, 0xffff0000, v17
	v_add_f32_e32 v140, v140, v144
	v_add_f32_e32 v141, v141, v145
	v_add_f32_e32 v142, v142, v146
	v_add_f32_e32 v143, v143, v147
	v_subrev_u32_e32 v152, 1, v148
	v_max_i32_e32 v152, 0, v152
	v_add_u32_e32 v149, 1, v148
	v_min_u32_e32 v149, 0x1000, v149
	v_sub_u32_e32 v149, v149, v152
	v_cvt_f32_i32_e32 v149, v149
	v_rcp_iflag_f32_e32 v149, v149
	v_lshlrev_b32_e32 v144, 16, v16
	v_and_b32_e32 v145, 0xffff0000, v16
	v_lshlrev_b32_e32 v146, 16, v17
	v_and_b32_e32 v147, 0xffff0000, v17
	v_fma_f32 v144, v149, v140, -v144
	v_fma_f32 v145, v149, v141, -v145
	v_fma_f32 v146, v149, v142, -v146
	v_fma_f32 v147, v149, v143, -v147
	v_cvt_pk_bf16_f32 v154, v144, v145
	v_cvt_pk_bf16_f32 v155, v146, v147
	ds_write_b64 v151, v[154:155] offset:36864
	v_lshlrev_b32_e32 v144, 16, v18
	v_and_b32_e32 v145, 0xffff0000, v18
	v_lshlrev_b32_e32 v146, 16, v19
	v_and_b32_e32 v147, 0xffff0000, v19
	v_add_f32_e32 v140, v140, v144
	v_add_f32_e32 v141, v141, v145
	v_add_f32_e32 v142, v142, v146
	v_add_f32_e32 v143, v143, v147
	v_lshlrev_b32_e32 v144, 16, v14
	v_and_b32_e32 v145, 0xffff0000, v14
	v_lshlrev_b32_e32 v146, 16, v15
	v_and_b32_e32 v147, 0xffff0000, v15
	v_sub_f32_e32 v140, v140, v144
	v_sub_f32_e32 v141, v141, v145
	v_sub_f32_e32 v142, v142, v146
	v_sub_f32_e32 v143, v143, v147
	v_add_u32_e32 v148, 1, v148
	v_subrev_u32_e32 v152, 1, v148
	v_max_i32_e32 v152, 0, v152
	v_add_u32_e32 v149, 1, v148
	v_min_u32_e32 v149, 0x1000, v149
	v_sub_u32_e32 v149, v149, v152
	v_cvt_f32_i32_e32 v149, v149
	v_rcp_iflag_f32_e32 v149, v149
	v_lshlrev_b32_e32 v144, 16, v18
	v_and_b32_e32 v145, 0xffff0000, v18
	v_lshlrev_b32_e32 v146, 16, v19
	v_and_b32_e32 v147, 0xffff0000, v19
	v_fma_f32 v144, v149, v140, -v144
	v_fma_f32 v145, v149, v141, -v145
	v_fma_f32 v146, v149, v142, -v146
	v_fma_f32 v147, v149, v143, -v147
	v_cvt_pk_bf16_f32 v154, v144, v145
	v_cvt_pk_bf16_f32 v155, v146, v147
	ds_write_b64 v151, v[154:155] offset:37136
	v_lshlrev_b32_e32 v144, 16, v20
	v_and_b32_e32 v145, 0xffff0000, v20
	v_lshlrev_b32_e32 v146, 16, v21
	v_and_b32_e32 v147, 0xffff0000, v21
	v_add_f32_e32 v140, v140, v144
	v_add_f32_e32 v141, v141, v145
	v_add_f32_e32 v142, v142, v146
	v_add_f32_e32 v143, v143, v147
; __device__ __forceinline__ float bf2f(bf16_t v) { return __uint_as_float((unsigned)v << 16); }
; __device__ __forceinline__ unsigned cvtpk(float lo, float hi) { f32x2_t v = {lo, hi}; bf16x2_t b = __builtin_convertvector(v, bf16x2_t); return __builtin_bit_cast(unsigned, b); }
; #define LAS __attribute__((address_space(3)))
; __device__ __forceinline__ void pool_units(const Ptrs& P, LAS unsigned char* lds, int bx, int G, int tid, int wave, int lane) {
;     ...
;         {
;             const int c = tid & 127, tl0 = (tid >> 7) * 32, w2 = 1 << g; const LAS bf16_t* U = (const LAS bf16_t*)(lds + PL_U) + c; float sum = 0.f;
;             for (int j = tl0 - w2; j < tl0 + w2; ++j) sum += bf2f(U[(j + 8) * 128]);
;             for (int tl = tl0; tl < tl0 + 32; ++tl) {
;                 const int ts = ts0 + tl, lo = ts - w2 < 0 ? 0 : ts - w2, hi = ts + w2 > SEQ ? SEQ : ts + w2;
;                 const float d = sum * __builtin_amdgcn_rcpf((float)(hi - lo)) - bf2f(U[(tl + 8) * 128]);
;                 *(LAS bf16_t*)(lds + PL_A + tl * PL_AP + c * 2) = (bf16_t)(cvtpk(d, 0.f) & 0xffffu);
;                 sum += bf2f(U[(tl + w2 + 8) * 128]) - bf2f(U[(tl - w2 + 8) * 128]);
;             }
;         }
	v_lshlrev_b32_e32 v144, 16, v16
	v_and_b32_e32 v145, 0xffff0000, v16
	v_lshlrev_b32_e32 v146, 16, v17
	v_and_b32_e32 v147, 0xffff0000, v17
	v_sub_f32_e32 v140, v140, v144
	v_sub_f32_e32 v141, v141, v145
	v_sub_f32_e32 v142, v142, v146
	v_sub_f32_e32 v143, v143, v147
	v_add_u32_e32 v148, 1, v148
	v_subrev_u32_e32 v152, 1, v148
	v_max_i32_e32 v152, 0, v152
	v_add_u32_e32 v149, 1, v148
	v_min_u32_e32 v149, 0x1000, v149
	v_sub_u32_e32 v149, v149, v152
	v_cvt_f32_i32_e32 v149, v149
	v_rcp_iflag_f32_e32 v149, v149
	v_lshlrev_b32_e32 v144, 16, v20
	v_and_b32_e32 v145, 0xffff0000, v20
	v_lshlrev_b32_e32 v146, 16, v21
	v_and_b32_e32 v147, 0xffff0000, v21
	v_fma_f32 v144, v149, v140, -v144
	v_fma_f32 v145, v149, v141, -v145
	v_fma_f32 v146, v149, v142, -v146
	v_fma_f32 v147, v149, v143, -v147
	v_cvt_pk_bf16_f32 v154, v144, v145
	v_cvt_pk_bf16_f32 v155, v146, v147
	ds_write_b64 v151, v[154:155] offset:37408
	v_lshlrev_b32_e32 v144, 16, v22
	v_and_b32_e32 v145, 0xffff0000, v22
	v_lshlrev_b32_e32 v146, 16, v23
	v_and_b32_e32 v147, 0xffff0000, v23
	v_add_f32_e32 v140, v140, v144
	v_add_f32_e32 v141, v141, v145
	v_add_f32_e32 v142, v142, v146
	v_add_f32_e32 v143, v143, v147
	v_lshlrev_b32_e32 v144, 16, v18
	v_and_b32_e32 v145, 0xffff0000, v18
	v_lshlrev_b32_e32 v146, 16, v19
	v_and_b32_e32 v147, 0xffff0000, v19
	v_sub_f32_e32 v140, v140, v144
	v_sub_f32_e32 v141, v141, v145
	v_sub_f32_e32 v142, v142, v146
	v_sub_f32_e32 v143, v143, v147
	v_add_u32_e32 v148, 1, v148
	v_subrev_u32_e32 v152, 1, v148
	v_max_i32_e32 v152, 0, v152
	v_add_u32_e32 v149, 1, v148
	v_min_u32_e32 v149, 0x1000, v149
	v_sub_u32_e32 v149, v149, v152
	v_cvt_f32_i32_e32 v149, v149
	v_rcp_iflag_f32_e32 v149, v149
	v_lshlrev_b32_e32 v144, 16, v22
	v_and_b32_e32 v145, 0xffff0000, v22
	v_lshlrev_b32_e32 v146, 16, v23
	v_and_b32_e32 v147, 0xffff0000, v23
	v_fma_f32 v144, v149, v140, -v144
	v_fma_f32 v145, v149, v141, -v145
	v_fma_f32 v146, v149, v142, -v146
	v_fma_f32 v147, v149, v143, -v147
	v_cvt_pk_bf16_f32 v154, v144, v145
	v_cvt_pk_bf16_f32 v155, v146, v147
	ds_write_b64 v151, v[154:155] offset:37680
	v_lshlrev_b32_e32 v144, 16, v24
	v_and_b32_e32 v145, 0xffff0000, v24
	v_lshlrev_b32_e32 v146, 16, v25
	v_and_b32_e32 v147, 0xffff0000, v25
	v_add_f32_e32 v140, v140, v144
	v_add_f32_e32 v141, v141, v145
	v_add_f32_e32 v142, v142, v146
	v_add_f32_e32 v143, v143, v147
	v_lshlrev_b32_e32 v144, 16, v20
	v_and_b32_e32 v145, 0xffff0000, v20
	v_lshlrev_b32_e32 v146, 16, v21
	v_and_b32_e32 v147, 0xffff0000, v21
	v_sub_f32_e32 v140, v140, v144
	v_sub_f32_e32 v141, v141, v145
	v_sub_f32_e32 v142, v142, v146
	v_sub_f32_e32 v143, v143, v147
	v_add_u32_e32 v148, 1, v148
	v_subrev_u32_e32 v152, 1, v148
	v_max_i32_e32 v152, 0, v152
	v_add_u32_e32 v149, 1, v148
	v_min_u32_e32 v149, 0x1000, v149
	v_sub_u32_e32 v149, v149, v152
	v_cvt_f32_i32_e32 v149, v149
	v_rcp_iflag_f32_e32 v149, v149
	v_lshlrev_b32_e32 v144, 16, v24
	v_and_b32_e32 v145, 0xffff0000, v24
	v_lshlrev_b32_e32 v146, 16, v25
	v_and_b32_e32 v147, 0xffff0000, v25
	v_fma_f32 v144, v149, v140, -v144
	v_fma_f32 v145, v149, v141, -v145
	v_fma_f32 v146, v149, v142, -v146
	v_fma_f32 v147, v149, v143, -v147
	v_cvt_pk_bf16_f32 v154, v144, v145
	v_cvt_pk_bf16_f32 v155, v146, v147
	ds_write_b64 v151, v[154:155] offset:37952
	v_lshlrev_b32_e32 v144, 16, v26
	v_and_b32_e32 v145, 0xffff0000, v26
	v_lshlrev_b32_e32 v146, 16, v27
	v_and_b32_e32 v147, 0xffff0000, v27
	v_add_f32_e32 v140, v140, v144
	v_add_f32_e32 v141, v141, v145
	v_add_f32_e32 v142, v142, v146
	v_add_f32_e32 v143, v143, v147
	v_lshlrev_b32_e32 v144, 16, v22
	v_and_b32_e32 v145, 0xffff0000, v22
	v_lshlrev_b32_e32 v146, 16, v23
	v_and_b32_e32 v147, 0xffff0000, v23
	v_sub_f32_e32 v140, v140, v144
	v_sub_f32_e32 v141, v141, v145
	v_sub_f32_e32 v142, v142, v146
	v_sub_f32_e32 v143, v143, v147
	v_add_u32_e32 v148, 1, v148
	v_subrev_u32_e32 v152, 1, v148
	v_max_i32_e32 v152, 0, v152
	v_add_u32_e32 v149, 1, v148
	v_min_u32_e32 v149, 0x1000, v149
	v_sub_u32_e32 v149, v149, v152
	v_cvt_f32_i32_e32 v149, v149
	v_rcp_iflag_f32_e32 v149, v149
	v_lshlrev_b32_e32 v144, 16, v26
	v_and_b32_e32 v145, 0xffff0000, v26
	v_lshlrev_b32_e32 v146, 16, v27
	v_and_b32_e32 v147, 0xffff0000, v27
	v_fma_f32 v144, v149, v140, -v144
	v_fma_f32 v145, v149, v141, -v145
	v_fma_f32 v146, v149, v142, -v146
	v_fma_f32 v147, v149, v143, -v147
	v_cvt_pk_bf16_f32 v154, v144, v145
	v_cvt_pk_bf16_f32 v155, v146, v147
	ds_write_b64 v151, v[154:155] offset:38224
	v_lshlrev_b32_e32 v144, 16, v28
	v_and_b32_e32 v145, 0xffff0000, v28
	v_lshlrev_b32_e32 v146, 16, v29
	v_and_b32_e32 v147, 0xffff0000, v29
	v_add_f32_e32 v140, v140, v144
	v_add_f32_e32 v141, v141, v145
	v_add_f32_e32 v142, v142, v146
	v_add_f32_e32 v143, v143, v147
	v_lshlrev_b32_e32 v144, 16, v24
	v_and_b32_e32 v145, 0xffff0000, v24
	v_lshlrev_b32_e32 v146, 16, v25
	v_and_b32_e32 v147, 0xffff0000, v25
	v_sub_f32_e32 v140, v140, v144
	v_sub_f32_e32 v141, v141, v145
	v_sub_f32_e32 v142, v142, v146
	v_sub_f32_e32 v143, v143, v147
	v_add_u32_e32 v148, 1, v148
	v_subrev_u32_e32 v152, 1, v148
	v_max_i32_e32 v152, 0, v152
	v_add_u32_e32 v149, 1, v148
	v_min_u32_e32 v149, 0x1000, v149
	v_sub_u32_e32 v149, v149, v152
	v_cvt_f32_i32_e32 v149, v149
	v_rcp_iflag_f32_e32 v149, v149
	v_lshlrev_b32_e32 v144, 16, v28
	v_and_b32_e32 v145, 0xffff0000, v28
	v_lshlrev_b32_e32 v146, 16, v29
	v_and_b32_e32 v147, 0xffff0000, v29
	v_fma_f32 v144, v149, v140, -v144
	v_fma_f32 v145, v149, v141, -v145
	v_fma_f32 v146, v149, v142, -v146
	v_fma_f32 v147, v149, v143, -v147
	v_cvt_pk_bf16_f32 v154, v144, v145
	v_cvt_pk_bf16_f32 v155, v146, v147
	ds_write_b64 v151, v[154:155] offset:38496
	v_lshlrev_b32_e32 v144, 16, v30
	v_and_b32_e32 v145, 0xffff0000, v30
	v_lshlrev_b32_e32 v146, 16, v31
	v_and_b32_e32 v147, 0xffff0000, v31
	v_add_f32_e32 v140, v140, v144
	v_add_f32_e32 v141, v141, v145
	v_add_f32_e32 v142, v142, v146
	v_add_f32_e32 v143, v143, v147
	v_lshlrev_b32_e32 v144, 16, v26
	v_and_b32_e32 v145, 0xffff0000, v26
	v_lshlrev_b32_e32 v146, 16, v27
	v_and_b32_e32 v147, 0xffff0000, v27
	v_sub_f32_e32 v140, v140, v144
	v_sub_f32_e32 v141, v141, v145
	v_sub_f32_e32 v142, v142, v146
	v_sub_f32_e32 v143, v143, v147
	v_add_u32_e32 v148, 1, v148
	v_subrev_u32_e32 v152, 1, v148
	v_max_i32_e32 v152, 0, v152
	v_add_u32_e32 v149, 1, v148
	v_min_u32_e32 v149, 0x1000, v149
	v_sub_u32_e32 v149, v149, v152
	v_cvt_f32_i32_e32 v149, v149
	v_rcp_iflag_f32_e32 v149, v149
	v_lshlrev_b32_e32 v144, 16, v30
	v_and_b32_e32 v145, 0xffff0000, v30
	v_lshlrev_b32_e32 v146, 16, v31
	v_and_b32_e32 v147, 0xffff0000, v31
	v_fma_f32 v144, v149, v140, -v144
	v_fma_f32 v145, v149, v141, -v145
	v_fma_f32 v146, v149, v142, -v146
	v_fma_f32 v147, v149, v143, -v147
	v_cvt_pk_bf16_f32 v154, v144, v145
	v_cvt_pk_bf16_f32 v155, v146, v147
	ds_write_b64 v151, v[154:155] offset:38768
.Lpw_done:
	s_lshl_b32 s6, s19, 8
	s_and_b64 vcc, exec, s[10:11]
	s_branch .Lpool_mfma
